# GEMM k-loop: waves 4-7 staggered by half a step (their per-step barrier sits after the first 16 MFMAs), so SIMD partners alternate LDS-read restart and MFMA work
# speedup vs baseline: 1.1012x; 1.0617x over previous
; DI void lds_barrier() { asm volatile("s_waitcnt lgkmcnt(0)\n\ts_barrier" ::: "memory"); }
; #define ISSUE() do { const int ka_ = (kp + koff >= nk) ? kp + koff - nk : kp + koff; \
;                 glds16x5(A + ka_ * 32, pbt + (size_t)(ka_ >> 1) * 16384 + (ka_ & 1) * 32, va, vb0, vb1, vb2, vb3, lbase + (unsigned)sp * H5_STAGE); \
;                 ++kp; if (kp == nk) { kp = 0; ++tp; pbt += (size_t)512 * K; if (tp == ntw) { tp = 0; pbt = Bt; } } sp = (sp == 2) ? 0 : sp + 1; } while (0)
; DI void run_jobs(const Params& P, int rb, int jj_lo, int jj_hi, unsigned char* smem) {
;     ...
; #pragma unroll
;                 for (int mt = 0; mt < 4; ++mt)
; #pragma unroll
;                     for (int n_ = 0; n_ < 8; ++n_) acc[mt][n_] = __builtin_amdgcn_mfma_f32_16x16x32_bf16(bfr[n_], af[mt], acc[mt][n_], 0, 0, 0);
;                 if (s + 2 < S) asm volatile("s_waitcnt vmcnt(5)" ::: "memory");
;                 else asm volatile("s_waitcnt vmcnt(0)" ::: "memory");
;                 lds_barrier();
;                 if (s + 3 < S) ISSUE();
.LBB0_144:
	s_cmp_eq_u32 s61, 0
	s_cbranch_scc1 .Lg_plain
	s_add_i32 s21, s61, 2
	s_cmp_ge_u32 s21, s54
	s_cbranch_scc1 .Lg_plain
	s_add_i32 s8, s53, s57
	s_cmp_ge_i32 s8, s52
	s_cselect_b32 s9, s52, 0
	s_sub_i32 s21, s8, s9
	s_lshl_b32 s8, s21, 5
	s_ashr_i32 s9, s8, 31
	s_lshl_b64 s[8:9], s[8:9], 1
	s_add_u32 s8, s28, s8
	s_addc_u32 s9, s29, s9
	s_ashr_i32 s64, s21, 1
	s_ashr_i32 s65, s64, 31
	s_lshl_b64 s[64:65], s[64:65], 15
	s_add_u32 s63, s4, s64
	s_addc_u32 s65, s58, s65
	s_lshl_b32 s21, s21, 14
	s_and_b32 s21, s21, 0x4000
	s_add_u32 s64, s63, s21
	s_mul_i32 s21, s23, 0xa000
	s_addc_u32 s65, s65, 0
	s_add_i32 s21, s21, s55
	s_mov_b32 m0, s21
	s_cmp_ge_u32 s55, 0x1000
	s_cbranch_scc1 .Lg_issue_y
	s_waitcnt lgkmcnt(10)
	v_mfma_f32_16x16x32_bf16 v[124:127], v[140:143], v[172:175], v[124:127]
	s_waitcnt lgkmcnt(9)
	v_mfma_f32_16x16x32_bf16 v[120:123], v[144:147], v[172:175], v[120:123]
	s_waitcnt lgkmcnt(8)
	v_mfma_f32_16x16x32_bf16 v[116:119], v[148:151], v[172:175], v[116:119]
	s_waitcnt lgkmcnt(7)
	v_mfma_f32_16x16x32_bf16 v[112:115], v[152:155], v[172:175], v[112:115]
	s_waitcnt lgkmcnt(6)
	v_mfma_f32_16x16x32_bf16 v[108:111], v[156:159], v[172:175], v[108:111]
	s_waitcnt lgkmcnt(5)
	v_mfma_f32_16x16x32_bf16 v[104:107], v[160:163], v[172:175], v[104:107]
	s_waitcnt lgkmcnt(4)
	v_mfma_f32_16x16x32_bf16 v[100:103], v[164:167], v[172:175], v[100:103]
	s_waitcnt lgkmcnt(3)
	v_mfma_f32_16x16x32_bf16 v[96:99], v[132:135], v[172:175], v[96:99]
	global_load_lds_dwordx4 v239, s[8:9]
	s_add_u32 m0, m0, 0x2000
	s_waitcnt lgkmcnt(2)
	v_mfma_f32_16x16x32_bf16 v[92:95], v[140:143], v[168:171], v[92:95]
	v_mfma_f32_16x16x32_bf16 v[88:91], v[144:147], v[168:171], v[88:91]
	v_mfma_f32_16x16x32_bf16 v[84:87], v[148:151], v[168:171], v[84:87]
	v_mfma_f32_16x16x32_bf16 v[80:83], v[152:155], v[168:171], v[80:83]
	global_load_lds_dwordx4 v237, s[64:65]
	s_add_u32 m0, m0, 0x2000
	v_mfma_f32_16x16x32_bf16 v[76:79], v[156:159], v[168:171], v[76:79]
	v_mfma_f32_16x16x32_bf16 v[72:75], v[160:163], v[168:171], v[72:75]
	v_mfma_f32_16x16x32_bf16 v[68:71], v[164:167], v[168:171], v[68:71]
	v_mfma_f32_16x16x32_bf16 v[64:67], v[132:135], v[168:171], v[64:67]
	global_load_lds_dwordx4 v240, s[64:65]
	s_add_u32 m0, m0, 0x2000
	s_waitcnt lgkmcnt(1)
	v_mfma_f32_16x16x32_bf16 v[60:63], v[140:143], v[136:139], v[60:63]
	v_mfma_f32_16x16x32_bf16 v[56:59], v[144:147], v[136:139], v[56:59]
	v_mfma_f32_16x16x32_bf16 v[52:55], v[148:151], v[136:139], v[52:55]
	v_mfma_f32_16x16x32_bf16 v[48:51], v[152:155], v[136:139], v[48:51]
	global_load_lds_dwordx4 v238, s[64:65]
	s_add_u32 m0, m0, 0x2000
	v_mfma_f32_16x16x32_bf16 v[44:47], v[156:159], v[136:139], v[44:47]
	v_mfma_f32_16x16x32_bf16 v[40:43], v[160:163], v[136:139], v[40:43]
	v_mfma_f32_16x16x32_bf16 v[36:39], v[164:167], v[136:139], v[36:39]
	v_mfma_f32_16x16x32_bf16 v[32:35], v[132:135], v[136:139], v[32:35]
	global_load_lds_dwordx4 v241, s[64:65]
	s_waitcnt lgkmcnt(0)
	v_mfma_f32_16x16x32_bf16 v[28:31], v[140:143], v[128:131], v[28:31]
	v_mfma_f32_16x16x32_bf16 v[24:27], v[144:147], v[128:131], v[24:27]
	v_mfma_f32_16x16x32_bf16 v[20:23], v[148:151], v[128:131], v[20:23]
	v_mfma_f32_16x16x32_bf16 v[16:19], v[152:155], v[128:131], v[16:19]
	v_mfma_f32_16x16x32_bf16 v[12:15], v[156:159], v[128:131], v[12:15]
	v_mfma_f32_16x16x32_bf16 v[8:11], v[160:163], v[128:131], v[8:11]
	v_mfma_f32_16x16x32_bf16 v[4:7], v[164:167], v[128:131], v[4:7]
	v_mfma_f32_16x16x32_bf16 v[0:3], v[132:135], v[128:131], v[0:3]
	s_add_i32 s21, s53, 1
	s_cmp_eq_u32 s21, s52
	s_cselect_b64 s[8:9], -1, 0
	s_add_i32 s53, s56, 1
	s_add_u32 s63, s4, s59
	s_addc_u32 s66, s58, 0
	s_cmp_eq_u32 s53, s22
	s_cselect_b64 s[64:65], -1, 0
	s_and_b64 s[64:65], s[64:65], exec
	s_cselect_b32 s63, s94, s63
	s_cselect_b32 s64, s95, s66
	s_cselect_b32 s53, 0, s53
	s_and_b64 s[8:9], s[8:9], exec
	s_cselect_b32 s58, s64, s58
	s_cselect_b32 s4, s63, s4
	s_cselect_b32 s56, s53, s56
	s_cselect_b32 s53, 0, s21
	s_add_i32 s8, s23, 1
	s_cmp_lg_u32 s23, 2
	s_cselect_b32 s23, s8, 0
	s_waitcnt vmcnt(5)
	s_waitcnt lgkmcnt(0)
	s_barrier
	s_branch .LBB0_150
; DI void lds_barrier() { asm volatile("s_waitcnt lgkmcnt(0)\n\ts_barrier" ::: "memory"); }
; #define ISSUE() do { const int ka_ = (kp + koff >= nk) ? kp + koff - nk : kp + koff; \
;                 glds16x5(A + ka_ * 32, pbt + (size_t)(ka_ >> 1) * 16384 + (ka_ & 1) * 32, va, vb0, vb1, vb2, vb3, lbase + (unsigned)sp * H5_STAGE); \
;                 ++kp; if (kp == nk) { kp = 0; ++tp; pbt += (size_t)512 * K; if (tp == ntw) { tp = 0; pbt = Bt; } } sp = (sp == 2) ? 0 : sp + 1; } while (0)
; DI void run_jobs(const Params& P, int rb, int jj_lo, int jj_hi, unsigned char* smem) {
;     ...
; #pragma unroll
;                 for (int mt = 0; mt < 4; ++mt)
; #pragma unroll
;                     for (int n_ = 0; n_ < 8; ++n_) acc[mt][n_] = __builtin_amdgcn_mfma_f32_16x16x32_bf16(bfr[n_], af[mt], acc[mt][n_], 0, 0, 0);
;                 if (s + 2 < S) asm volatile("s_waitcnt vmcnt(5)" ::: "memory");
;                 else asm volatile("s_waitcnt vmcnt(0)" ::: "memory");
;                 lds_barrier();
;                 if (s + 3 < S) ISSUE();
.Lg_issue_y:
	s_waitcnt lgkmcnt(10)
	v_mfma_f32_16x16x32_bf16 v[124:127], v[140:143], v[172:175], v[124:127]
	s_waitcnt lgkmcnt(9)
	v_mfma_f32_16x16x32_bf16 v[120:123], v[144:147], v[172:175], v[120:123]
	s_waitcnt lgkmcnt(8)
	v_mfma_f32_16x16x32_bf16 v[116:119], v[148:151], v[172:175], v[116:119]
	s_waitcnt lgkmcnt(7)
	v_mfma_f32_16x16x32_bf16 v[112:115], v[152:155], v[172:175], v[112:115]
	s_waitcnt lgkmcnt(6)
	v_mfma_f32_16x16x32_bf16 v[108:111], v[156:159], v[172:175], v[108:111]
	s_waitcnt lgkmcnt(5)
	v_mfma_f32_16x16x32_bf16 v[104:107], v[160:163], v[172:175], v[104:107]
	s_waitcnt lgkmcnt(4)
	v_mfma_f32_16x16x32_bf16 v[100:103], v[164:167], v[172:175], v[100:103]
	s_waitcnt lgkmcnt(3)
	v_mfma_f32_16x16x32_bf16 v[96:99], v[132:135], v[172:175], v[96:99]
	global_load_lds_dwordx4 v239, s[8:9]
	s_add_u32 m0, m0, 0x2000
	s_waitcnt lgkmcnt(2)
	v_mfma_f32_16x16x32_bf16 v[92:95], v[140:143], v[168:171], v[92:95]
	v_mfma_f32_16x16x32_bf16 v[88:91], v[144:147], v[168:171], v[88:91]
	global_load_lds_dwordx4 v237, s[64:65]
	s_add_u32 m0, m0, 0x2000
	v_mfma_f32_16x16x32_bf16 v[84:87], v[148:151], v[168:171], v[84:87]
	v_mfma_f32_16x16x32_bf16 v[80:83], v[152:155], v[168:171], v[80:83]
	global_load_lds_dwordx4 v240, s[64:65]
	s_add_u32 m0, m0, 0x2000
	v_mfma_f32_16x16x32_bf16 v[76:79], v[156:159], v[168:171], v[76:79]
	v_mfma_f32_16x16x32_bf16 v[72:75], v[160:163], v[168:171], v[72:75]
	global_load_lds_dwordx4 v238, s[64:65]
	s_add_u32 m0, m0, 0x2000
	v_mfma_f32_16x16x32_bf16 v[68:71], v[164:167], v[168:171], v[68:71]
	v_mfma_f32_16x16x32_bf16 v[64:67], v[132:135], v[168:171], v[64:67]
	global_load_lds_dwordx4 v241, s[64:65]
	s_waitcnt vmcnt(5)
	s_waitcnt lgkmcnt(0)
	s_barrier
	s_waitcnt lgkmcnt(1)
	v_mfma_f32_16x16x32_bf16 v[60:63], v[140:143], v[136:139], v[60:63]
	v_mfma_f32_16x16x32_bf16 v[56:59], v[144:147], v[136:139], v[56:59]
	v_mfma_f32_16x16x32_bf16 v[52:55], v[148:151], v[136:139], v[52:55]
	v_mfma_f32_16x16x32_bf16 v[48:51], v[152:155], v[136:139], v[48:51]
	v_mfma_f32_16x16x32_bf16 v[44:47], v[156:159], v[136:139], v[44:47]
	v_mfma_f32_16x16x32_bf16 v[40:43], v[160:163], v[136:139], v[40:43]
	v_mfma_f32_16x16x32_bf16 v[36:39], v[164:167], v[136:139], v[36:39]
	v_mfma_f32_16x16x32_bf16 v[32:35], v[132:135], v[136:139], v[32:35]
	s_waitcnt lgkmcnt(0)
	v_mfma_f32_16x16x32_bf16 v[28:31], v[140:143], v[128:131], v[28:31]
	v_mfma_f32_16x16x32_bf16 v[24:27], v[144:147], v[128:131], v[24:27]
	v_mfma_f32_16x16x32_bf16 v[20:23], v[148:151], v[128:131], v[20:23]
	v_mfma_f32_16x16x32_bf16 v[16:19], v[152:155], v[128:131], v[16:19]
	v_mfma_f32_16x16x32_bf16 v[12:15], v[156:159], v[128:131], v[12:15]
	v_mfma_f32_16x16x32_bf16 v[8:11], v[160:163], v[128:131], v[8:11]
	v_mfma_f32_16x16x32_bf16 v[4:7], v[164:167], v[128:131], v[4:7]
	v_mfma_f32_16x16x32_bf16 v[0:3], v[132:135], v[128:131], v[0:3]
	s_add_i32 s21, s53, 1
	s_cmp_eq_u32 s21, s52
	s_cselect_b64 s[8:9], -1, 0
	s_add_i32 s53, s56, 1
	s_add_u32 s63, s4, s59
	s_addc_u32 s66, s58, 0
	s_cmp_eq_u32 s53, s22
	s_cselect_b64 s[64:65], -1, 0
	s_and_b64 s[64:65], s[64:65], exec
	s_cselect_b32 s63, s94, s63
	s_cselect_b32 s64, s95, s66
	s_cselect_b32 s53, 0, s53
	s_and_b64 s[8:9], s[8:9], exec
	s_cselect_b32 s58, s64, s58
	s_cselect_b32 s4, s63, s4
	s_cselect_b32 s56, s53, s56
	s_cselect_b32 s53, 0, s21
	s_add_i32 s8, s23, 1
	s_cmp_lg_u32 s23, 2
	s_cselect_b32 s23, s8, 0
	s_branch .LBB0_150
.Lg_plain:
	s_nop 0
	s_add_i32 s21, s61, 2
	s_cmp_ge_u32 s21, s54
	s_cselect_b32 s21, 1, 0
	s_cmp_ge_u32 s55, 0x1000
	s_cbranch_scc1 .Lg_plain_y
	s_waitcnt lgkmcnt(10)
	v_mfma_f32_16x16x32_bf16 v[124:127], v[140:143], v[172:175], v[124:127]
	s_waitcnt lgkmcnt(9)
	v_mfma_f32_16x16x32_bf16 v[120:123], v[144:147], v[172:175], v[120:123]
	s_waitcnt lgkmcnt(8)
	v_mfma_f32_16x16x32_bf16 v[116:119], v[148:151], v[172:175], v[116:119]
	s_waitcnt lgkmcnt(7)
	v_mfma_f32_16x16x32_bf16 v[112:115], v[152:155], v[172:175], v[112:115]
	s_waitcnt lgkmcnt(6)
	v_mfma_f32_16x16x32_bf16 v[108:111], v[156:159], v[172:175], v[108:111]
	s_waitcnt lgkmcnt(5)
	v_mfma_f32_16x16x32_bf16 v[104:107], v[160:163], v[172:175], v[104:107]
	s_waitcnt lgkmcnt(4)
	v_mfma_f32_16x16x32_bf16 v[100:103], v[164:167], v[172:175], v[100:103]
	s_waitcnt lgkmcnt(3)
	v_mfma_f32_16x16x32_bf16 v[96:99], v[132:135], v[172:175], v[96:99]
	s_waitcnt lgkmcnt(2)
	v_mfma_f32_16x16x32_bf16 v[92:95], v[140:143], v[168:171], v[92:95]
	v_mfma_f32_16x16x32_bf16 v[88:91], v[144:147], v[168:171], v[88:91]
	v_mfma_f32_16x16x32_bf16 v[84:87], v[148:151], v[168:171], v[84:87]
	v_mfma_f32_16x16x32_bf16 v[80:83], v[152:155], v[168:171], v[80:83]
	v_mfma_f32_16x16x32_bf16 v[76:79], v[156:159], v[168:171], v[76:79]
	v_mfma_f32_16x16x32_bf16 v[72:75], v[160:163], v[168:171], v[72:75]
	v_mfma_f32_16x16x32_bf16 v[68:71], v[164:167], v[168:171], v[68:71]
	v_mfma_f32_16x16x32_bf16 v[64:67], v[132:135], v[168:171], v[64:67]
	s_waitcnt lgkmcnt(1)
	v_mfma_f32_16x16x32_bf16 v[60:63], v[140:143], v[136:139], v[60:63]
	v_mfma_f32_16x16x32_bf16 v[56:59], v[144:147], v[136:139], v[56:59]
	v_mfma_f32_16x16x32_bf16 v[52:55], v[148:151], v[136:139], v[52:55]
	v_mfma_f32_16x16x32_bf16 v[48:51], v[152:155], v[136:139], v[48:51]
	v_mfma_f32_16x16x32_bf16 v[44:47], v[156:159], v[136:139], v[44:47]
	v_mfma_f32_16x16x32_bf16 v[40:43], v[160:163], v[136:139], v[40:43]
	v_mfma_f32_16x16x32_bf16 v[36:39], v[164:167], v[136:139], v[36:39]
	v_mfma_f32_16x16x32_bf16 v[32:35], v[132:135], v[136:139], v[32:35]
	s_waitcnt lgkmcnt(0)
	v_mfma_f32_16x16x32_bf16 v[28:31], v[140:143], v[128:131], v[28:31]
	v_mfma_f32_16x16x32_bf16 v[24:27], v[144:147], v[128:131], v[24:27]
	v_mfma_f32_16x16x32_bf16 v[20:23], v[148:151], v[128:131], v[20:23]
	v_mfma_f32_16x16x32_bf16 v[16:19], v[152:155], v[128:131], v[16:19]
	v_mfma_f32_16x16x32_bf16 v[12:15], v[156:159], v[128:131], v[12:15]
	v_mfma_f32_16x16x32_bf16 v[8:11], v[160:163], v[128:131], v[8:11]
	v_mfma_f32_16x16x32_bf16 v[4:7], v[164:167], v[128:131], v[4:7]
	v_mfma_f32_16x16x32_bf16 v[0:3], v[132:135], v[128:131], v[0:3]
	s_cmp_eq_u32 s21, 0
	s_cbranch_scc0 .Lg_drain_x
	s_waitcnt vmcnt(5)
	s_branch .Lg_bar_x

; DI void lds_barrier() { asm volatile("s_waitcnt lgkmcnt(0)\n\ts_barrier" ::: "memory"); }
; DI void run_jobs(const Params& P, int rb, int jj_lo, int jj_hi, unsigned char* smem) {
;     ...
; #pragma unroll
;                 for (int mt = 0; mt < 4; ++mt)
; #pragma unroll
;                     for (int n_ = 0; n_ < 8; ++n_) acc[mt][n_] = __builtin_amdgcn_mfma_f32_16x16x32_bf16(bfr[n_], af[mt], acc[mt][n_], 0, 0, 0);
;                 if (s + 2 < S) asm volatile("s_waitcnt vmcnt(5)" ::: "memory");
;                 else asm volatile("s_waitcnt vmcnt(0)" ::: "memory");
;                 lds_barrier();
.Lg_bar_x:
	s_waitcnt lgkmcnt(0)
	s_barrier
	s_branch .LBB0_150
.Lg_plain_y:
	s_waitcnt lgkmcnt(10)
	v_mfma_f32_16x16x32_bf16 v[124:127], v[140:143], v[172:175], v[124:127]
	s_waitcnt lgkmcnt(9)
	v_mfma_f32_16x16x32_bf16 v[120:123], v[144:147], v[172:175], v[120:123]
	s_waitcnt lgkmcnt(8)
	v_mfma_f32_16x16x32_bf16 v[116:119], v[148:151], v[172:175], v[116:119]
	s_waitcnt lgkmcnt(7)
	v_mfma_f32_16x16x32_bf16 v[112:115], v[152:155], v[172:175], v[112:115]
	s_waitcnt lgkmcnt(6)
	v_mfma_f32_16x16x32_bf16 v[108:111], v[156:159], v[172:175], v[108:111]
	s_waitcnt lgkmcnt(5)
	v_mfma_f32_16x16x32_bf16 v[104:107], v[160:163], v[172:175], v[104:107]
	s_waitcnt lgkmcnt(4)
	v_mfma_f32_16x16x32_bf16 v[100:103], v[164:167], v[172:175], v[100:103]
	s_waitcnt lgkmcnt(3)
	v_mfma_f32_16x16x32_bf16 v[96:99], v[132:135], v[172:175], v[96:99]
	s_waitcnt lgkmcnt(2)
	v_mfma_f32_16x16x32_bf16 v[92:95], v[140:143], v[168:171], v[92:95]
	v_mfma_f32_16x16x32_bf16 v[88:91], v[144:147], v[168:171], v[88:91]
	v_mfma_f32_16x16x32_bf16 v[84:87], v[148:151], v[168:171], v[84:87]
	v_mfma_f32_16x16x32_bf16 v[80:83], v[152:155], v[168:171], v[80:83]
	v_mfma_f32_16x16x32_bf16 v[76:79], v[156:159], v[168:171], v[76:79]
	v_mfma_f32_16x16x32_bf16 v[72:75], v[160:163], v[168:171], v[72:75]
	v_mfma_f32_16x16x32_bf16 v[68:71], v[164:167], v[168:171], v[68:71]
	v_mfma_f32_16x16x32_bf16 v[64:67], v[132:135], v[168:171], v[64:67]
	s_cmp_eq_u32 s21, 0
	s_cbranch_scc0 .Lg_drain_y
	s_waitcnt vmcnt(5)
	s_branch .Lg_bar_y

; DI void lds_barrier() { asm volatile("s_waitcnt lgkmcnt(0)\n\ts_barrier" ::: "memory"); }
; #define ISSUE() do { const int ka_ = (kp + koff >= nk) ? kp + koff - nk : kp + koff; \
;                 glds16x5(A + ka_ * 32, pbt + (size_t)(ka_ >> 1) * 16384 + (ka_ & 1) * 32, va, vb0, vb1, vb2, vb3, lbase + (unsigned)sp * H5_STAGE); \
;                 ++kp; if (kp == nk) { kp = 0; ++tp; pbt += (size_t)512 * K; if (tp == ntw) { tp = 0; pbt = Bt; } } sp = (sp == 2) ? 0 : sp + 1; } while (0)
; DI void run_jobs(const Params& P, int rb, int jj_lo, int jj_hi, unsigned char* smem) {
;     ...
; #pragma unroll
;                 for (int mt = 0; mt < 4; ++mt)
; #pragma unroll
;                     for (int n_ = 0; n_ < 8; ++n_) acc[mt][n_] = __builtin_amdgcn_mfma_f32_16x16x32_bf16(bfr[n_], af[mt], acc[mt][n_], 0, 0, 0);
;                 if (s + 2 < S) asm volatile("s_waitcnt vmcnt(5)" ::: "memory");
;                 else asm volatile("s_waitcnt vmcnt(0)" ::: "memory");
;                 lds_barrier();
;                 if (s + 3 < S) ISSUE();
;                 st = (st == 2) ? 0 : st + 1;
;                 ++kt;
;                 if (kt == nk) {
.Lg_bar_y:
	s_waitcnt lgkmcnt(0)
	s_barrier
	s_waitcnt lgkmcnt(1)
	v_mfma_f32_16x16x32_bf16 v[60:63], v[140:143], v[136:139], v[60:63]
	v_mfma_f32_16x16x32_bf16 v[56:59], v[144:147], v[136:139], v[56:59]
	v_mfma_f32_16x16x32_bf16 v[52:55], v[148:151], v[136:139], v[52:55]
	v_mfma_f32_16x16x32_bf16 v[48:51], v[152:155], v[136:139], v[48:51]
	v_mfma_f32_16x16x32_bf16 v[44:47], v[156:159], v[136:139], v[44:47]
	v_mfma_f32_16x16x32_bf16 v[40:43], v[160:163], v[136:139], v[40:43]
	v_mfma_f32_16x16x32_bf16 v[36:39], v[164:167], v[136:139], v[36:39]
	v_mfma_f32_16x16x32_bf16 v[32:35], v[132:135], v[136:139], v[32:35]
	s_waitcnt lgkmcnt(0)
	v_mfma_f32_16x16x32_bf16 v[28:31], v[140:143], v[128:131], v[28:31]
	v_mfma_f32_16x16x32_bf16 v[24:27], v[144:147], v[128:131], v[24:27]
	v_mfma_f32_16x16x32_bf16 v[20:23], v[148:151], v[128:131], v[20:23]
	v_mfma_f32_16x16x32_bf16 v[16:19], v[152:155], v[128:131], v[16:19]
	v_mfma_f32_16x16x32_bf16 v[12:15], v[156:159], v[128:131], v[12:15]
	v_mfma_f32_16x16x32_bf16 v[8:11], v[160:163], v[128:131], v[8:11]
	v_mfma_f32_16x16x32_bf16 v[4:7], v[164:167], v[128:131], v[4:7]
	v_mfma_f32_16x16x32_bf16 v[0:3], v[132:135], v[128:131], v[0:3]
.LBB0_150:
	s_add_i32 s20, s20, 1
	s_cmp_lg_u32 s20, s52
	s_cbranch_scc1 .LBB0_141
	s_nop 7
	s_nop 7
	s_and_b64 vcc, exec, s[12:13]
	s_cbranch_vccz .LBB0_155
	s_cmp_lt_i32 s15, 3
	s_cbranch_scc1 .LBB0_156
	s_cmp_gt_i32 s15, 4
	s_cbranch_scc0 .LBB0_157
	s_cmp_lg_u32 s15, 5
	s_mov_b64 s[8:9], -1
	s_cselect_b64 s[20:21], -1, 0
	s_cbranch_execz .LBB0_158
	s_branch .LBB0_159
